# ffn_out prompt rows also as 256x128 double tiles with batched residual epilogue
# speedup vs baseline: 1.0235x; 1.0090x over previous
.LBB0_2414:
	s_lshl_b32 s16, s12, 3
	v_readlane_b32 s6, v249, 52
	s_mul_i32 s0, s72, 0xb00
	s_mov_b32 s1, s73
	s_cmp_ge_i32 s14, s16
	s_mul_hi_u32 s10, s6, 0x580000
	s_mul_i32 s11, s6, 0x580000
	v_readlane_b32 s7, v249, 53
	s_cbranch_scc1 .LBB0_2422
	s_lshr_b32 s17, s12, 3
	s_lshl_b64 s[6:7], s[0:1], 1
	s_waitcnt lgkmcnt(0)
	s_add_u32 s18, s8, s6
	s_addc_u32 s19, s9, s7
	v_and_b32_e32 v2, 15, v0
	v_ashrrev_i32_e32 v3, 1, v0
	s_movk_i32 s20, 0xffc0
	s_cmp_lt_i32 s13, 0
	v_and_or_b32 v74, v3, s20, v2
	v_lshrrev_b32_e32 v2, 2, v0
	s_cselect_b64 s[6:7], -1, 0
	v_and_b32_e32 v2, 12, v2
	s_add_u32 s20, s8, s11
	v_and_or_b32 v75, v0, 64, v2
	s_addc_u32 s21, s9, s10
	v_readlane_b32 s24, v249, 1
	s_nop 0
	s_cmpk_lg_u32 s24, 0x200
	s_cbranch_scc1 .LBB0_2417
	s_load_dwordx2 s[38:39], s[84:85], 0x130
	v_readlane_b32 s24, v249, 0
	s_nop 0
	s_and_b32 s25, s24, 7
	s_lshr_b32 s24, s24, 3
	s_and_b32 s27, s24, 7
	s_lshr_b32 s24, s24, 3
	s_and_b32 s28, s24, 3
	s_lshr_b32 s24, s24, 2
	s_lshl_b32 s24, s24, 3
	s_add_i32 s24, s24, s28
	s_lshl_b32 s24, s24, 3
	s_add_i32 s28, s24, s25
	s_add_i32 s29, s28, 32
	s_mul_i32 s24, s28, 0xb0000
	s_add_u32 s30, s4, s24
	s_addc_u32 s31, s5, 0
	s_mul_i32 s24, s29, 0xb0000
	s_add_u32 s44, s4, s24
	s_addc_u32 s45, s5, 0
	s_mul_i32 s24, s27, 0xb0000
	s_add_u32 s34, s20, s24
	s_addc_u32 s35, s21, 0
	s_waitcnt lgkmcnt(0)
	s_lshl_b32 s27, s27, 9
	s_lshl_b32 s24, s28, 19
	s_add_i32 s24, s24, s27
	s_add_u32 s40, s38, s24
	s_addc_u32 s41, s39, 0
	s_lshl_b32 s24, s29, 19
	s_add_i32 s24, s24, s27
	s_add_u32 s42, s38, s24
	s_addc_u32 s43, s39, 0
	v_and_b32_e32 v144, 7, v196
	v_bfe_u32 v145, v196, 4, 2
	v_bfe_u32 v146, v196, 6, 1
	v_lshl_or_b32 v147, v146, 2, v145
	v_xor_b32_e32 v144, v144, v147
	v_lshrrev_b32_e32 v147, 3, v196
	v_mul_u32_u24_e32 v147, 0x1600, v147
	v_lshl_or_b32 v136, v144, 4, v147
	v_add_u32_e32 v137, 0x2c000, v136
	v_add_u32_e32 v138, 0x58000, v136
	v_add_u32_e32 v139, 0x84000, v136
	v_and_b32_e32 v144, 15, v196
	v_bfe_u32 v147, v196, 1, 3
	v_xor_b32_e32 v147, v145, v147
	v_lshlrev_b32_e32 v147, 4, v147
	v_xor_b32_e32 v130, 64, v147
	v_lshlrev_b32_e32 v144, 7, v144
	v_lshrrev_b32_e32 v131, 7, v196
	v_lshl_or_b32 v131, v131, 13, v144
	v_lshl_or_b32 v133, v146, 13, v144
	v_add_u32_e32 v140, v131, v147
	v_add_u32_e32 v141, v131, v130
	v_add_u32_e32 v142, v133, v147
	v_add_u32_e32 v143, v133, v130
	v_readfirstlane_b32 s36, v196
	s_lshr_b32 s36, s36, 6
	s_lshl_b32 s36, s36, 10
	s_barrier
	s_add_i32 m0, s36, 0x0
	s_nop 0
	global_load_lds_dwordx4 v136, s[30:31]
	s_add_i32 m0, s36, 0x1000
	s_nop 0
	global_load_lds_dwordx4 v137, s[30:31]
	s_add_i32 m0, s36, 0x2000
	s_nop 0
	global_load_lds_dwordx4 v138, s[30:31]
	s_add_i32 m0, s36, 0x3000
	s_nop 0
	global_load_lds_dwordx4 v139, s[30:31]
	s_add_i32 m0, s36, 0x4000
	s_nop 0
	global_load_lds_dwordx4 v136, s[44:45]
	s_add_i32 m0, s36, 0x5000
	s_nop 0
	global_load_lds_dwordx4 v137, s[44:45]
	s_add_i32 m0, s36, 0x6000
	s_nop 0
	global_load_lds_dwordx4 v138, s[44:45]
	s_add_i32 m0, s36, 0x7000
	s_nop 0
	global_load_lds_dwordx4 v139, s[44:45]
	s_add_u32 s30, s30, 0x80
	s_addc_u32 s31, s31, 0
	s_add_u32 s44, s44, 0x80
	s_addc_u32 s45, s45, 0
	s_add_i32 m0, s36, 0x8000
	s_nop 0
	global_load_lds_dwordx4 v136, s[34:35]
	s_add_i32 m0, s36, 0x9000
	s_nop 0
	global_load_lds_dwordx4 v137, s[34:35]
	s_add_i32 m0, s36, 0xa000
	s_nop 0
	global_load_lds_dwordx4 v138, s[34:35]
	s_add_i32 m0, s36, 0xb000
	s_nop 0
	global_load_lds_dwordx4 v139, s[34:35]
	s_add_u32 s34, s34, 0x80
	s_addc_u32 s35, s35, 0
	v_mov_b64_e32 v[62:63], 0
	v_mov_b64_e32 v[64:65], 0
	v_mov_b64_e32 v[58:59], 0
	v_mov_b64_e32 v[60:61], 0
	v_mov_b64_e32 v[54:55], 0
	v_mov_b64_e32 v[56:57], 0
	v_mov_b64_e32 v[50:51], 0
	v_mov_b64_e32 v[52:53], 0
	v_mov_b64_e32 v[46:47], 0
	v_mov_b64_e32 v[48:49], 0
	v_mov_b64_e32 v[42:43], 0
	v_mov_b64_e32 v[44:45], 0
	v_mov_b64_e32 v[38:39], 0
	v_mov_b64_e32 v[40:41], 0
	v_mov_b64_e32 v[34:35], 0
	v_mov_b64_e32 v[36:37], 0
	v_mov_b64_e32 v[30:31], 0
	v_mov_b64_e32 v[32:33], 0
	v_mov_b64_e32 v[26:27], 0
	v_mov_b64_e32 v[28:29], 0
	v_mov_b64_e32 v[22:23], 0
	v_mov_b64_e32 v[24:25], 0
	v_mov_b64_e32 v[18:19], 0
	v_mov_b64_e32 v[20:21], 0
	v_mov_b64_e32 v[14:15], 0
	v_mov_b64_e32 v[16:17], 0
	v_mov_b64_e32 v[10:11], 0
	v_mov_b64_e32 v[12:13], 0
	v_mov_b64_e32 v[6:7], 0
	v_mov_b64_e32 v[8:9], 0
	v_mov_b64_e32 v[2:3], 0
	v_mov_b64_e32 v[4:5], 0
	v_mov_b64_e32 v[66:67], 0
	v_mov_b64_e32 v[68:69], 0
	v_mov_b64_e32 v[70:71], 0
	v_mov_b64_e32 v[72:73], 0
	v_mov_b64_e32 v[74:75], 0
	v_mov_b64_e32 v[76:77], 0
	v_mov_b64_e32 v[78:79], 0
	v_mov_b64_e32 v[80:81], 0
	v_mov_b64_e32 v[82:83], 0
	v_mov_b64_e32 v[84:85], 0
	v_mov_b64_e32 v[86:87], 0
	v_mov_b64_e32 v[88:89], 0
	v_mov_b64_e32 v[90:91], 0
	v_mov_b64_e32 v[92:93], 0
	v_mov_b64_e32 v[94:95], 0
	v_mov_b64_e32 v[96:97], 0
	v_mov_b64_e32 v[98:99], 0
	v_mov_b64_e32 v[100:101], 0
	v_mov_b64_e32 v[102:103], 0
	v_mov_b64_e32 v[104:105], 0
	v_mov_b64_e32 v[106:107], 0
	v_mov_b64_e32 v[108:109], 0
	v_mov_b64_e32 v[110:111], 0
	v_mov_b64_e32 v[112:113], 0
	v_mov_b64_e32 v[114:115], 0
	v_mov_b64_e32 v[116:117], 0
	v_mov_b64_e32 v[118:119], 0
	v_mov_b64_e32 v[120:121], 0
	v_mov_b64_e32 v[122:123], 0
	v_mov_b64_e32 v[124:125], 0
	v_mov_b64_e32 v[126:127], 0
	v_mov_b64_e32 v[128:129], 0
	s_movk_i32 s37, 21
.Lr2o_k:
	s_waitcnt vmcnt(0)
	s_barrier
	s_add_i32 m0, s36, 0xc000
	s_nop 0
	global_load_lds_dwordx4 v136, s[34:35]
	s_add_i32 m0, s36, 0xd000
	s_nop 0
	global_load_lds_dwordx4 v137, s[34:35]
	s_add_i32 m0, s36, 0xe000
	s_nop 0
	global_load_lds_dwordx4 v138, s[34:35]
	s_add_i32 m0, s36, 0xf000
	s_nop 0
	global_load_lds_dwordx4 v139, s[34:35]
	s_add_u32 s34, s34, 0x80
	s_addc_u32 s35, s35, 0
	ds_read_b128 v[148:151], v140 offset:0
	ds_read_b128 v[152:155], v140 offset:2048
	ds_read_b128 v[156:159], v140 offset:4096
	ds_read_b128 v[160:163], v140 offset:6144
	ds_read_b128 v[164:167], v140 offset:16384
	ds_read_b128 v[168:171], v140 offset:18432
	ds_read_b128 v[174:177], v140 offset:20480
	ds_read_b128 v[182:185], v140 offset:22528
	ds_read_b128 v[188:191], v142 offset:32768
	ds_read_b128 v[192:195], v142 offset:34816
	ds_read_b128 v[208:211], v142 offset:36864
	ds_read_b128 v[212:215], v142 offset:38912
	s_waitcnt lgkmcnt(0)
	s_setprio 1
	v_mfma_f32_16x16x32_bf16 v[62:65], v[188:191], v[148:151], v[62:65]
	v_mfma_f32_16x16x32_bf16 v[58:61], v[192:195], v[148:151], v[58:61]
	v_mfma_f32_16x16x32_bf16 v[54:57], v[208:211], v[148:151], v[54:57]
	v_mfma_f32_16x16x32_bf16 v[50:53], v[212:215], v[148:151], v[50:53]
	v_mfma_f32_16x16x32_bf16 v[46:49], v[188:191], v[152:155], v[46:49]
	v_mfma_f32_16x16x32_bf16 v[42:45], v[192:195], v[152:155], v[42:45]
	v_mfma_f32_16x16x32_bf16 v[38:41], v[208:211], v[152:155], v[38:41]
	v_mfma_f32_16x16x32_bf16 v[34:37], v[212:215], v[152:155], v[34:37]
	v_mfma_f32_16x16x32_bf16 v[30:33], v[188:191], v[156:159], v[30:33]
	v_mfma_f32_16x16x32_bf16 v[26:29], v[192:195], v[156:159], v[26:29]
	v_mfma_f32_16x16x32_bf16 v[22:25], v[208:211], v[156:159], v[22:25]
	v_mfma_f32_16x16x32_bf16 v[18:21], v[212:215], v[156:159], v[18:21]
	v_mfma_f32_16x16x32_bf16 v[14:17], v[188:191], v[160:163], v[14:17]
	v_mfma_f32_16x16x32_bf16 v[10:13], v[192:195], v[160:163], v[10:13]
	v_mfma_f32_16x16x32_bf16 v[6:9], v[208:211], v[160:163], v[6:9]
	v_mfma_f32_16x16x32_bf16 v[2:5], v[212:215], v[160:163], v[2:5]
	v_mfma_f32_16x16x32_bf16 v[66:69], v[188:191], v[164:167], v[66:69]
	v_mfma_f32_16x16x32_bf16 v[70:73], v[192:195], v[164:167], v[70:73]
	v_mfma_f32_16x16x32_bf16 v[74:77], v[208:211], v[164:167], v[74:77]
	v_mfma_f32_16x16x32_bf16 v[78:81], v[212:215], v[164:167], v[78:81]
	v_mfma_f32_16x16x32_bf16 v[82:85], v[188:191], v[168:171], v[82:85]
	v_mfma_f32_16x16x32_bf16 v[86:89], v[192:195], v[168:171], v[86:89]
	v_mfma_f32_16x16x32_bf16 v[90:93], v[208:211], v[168:171], v[90:93]
	v_mfma_f32_16x16x32_bf16 v[94:97], v[212:215], v[168:171], v[94:97]
	v_mfma_f32_16x16x32_bf16 v[98:101], v[188:191], v[174:177], v[98:101]
	v_mfma_f32_16x16x32_bf16 v[102:105], v[192:195], v[174:177], v[102:105]
	v_mfma_f32_16x16x32_bf16 v[106:109], v[208:211], v[174:177], v[106:109]
	v_mfma_f32_16x16x32_bf16 v[110:113], v[212:215], v[174:177], v[110:113]
	v_mfma_f32_16x16x32_bf16 v[114:117], v[188:191], v[182:185], v[114:117]
	v_mfma_f32_16x16x32_bf16 v[118:121], v[192:195], v[182:185], v[118:121]
	v_mfma_f32_16x16x32_bf16 v[122:125], v[208:211], v[182:185], v[122:125]
	v_mfma_f32_16x16x32_bf16 v[126:129], v[212:215], v[182:185], v[126:129]
	s_setprio 0
	ds_read_b128 v[148:151], v141 offset:0
	ds_read_b128 v[152:155], v141 offset:2048
	ds_read_b128 v[156:159], v141 offset:4096
	ds_read_b128 v[160:163], v141 offset:6144
	ds_read_b128 v[164:167], v141 offset:16384
	ds_read_b128 v[168:171], v141 offset:18432
	ds_read_b128 v[174:177], v141 offset:20480
	ds_read_b128 v[182:185], v141 offset:22528
	ds_read_b128 v[188:191], v143 offset:32768
	ds_read_b128 v[192:195], v143 offset:34816
	ds_read_b128 v[208:211], v143 offset:36864
	ds_read_b128 v[212:215], v143 offset:38912
	s_waitcnt lgkmcnt(0)
	s_barrier
	s_add_i32 m0, s36, 0x0
	s_nop 0
	global_load_lds_dwordx4 v136, s[30:31]
	s_add_i32 m0, s36, 0x1000
	s_nop 0
	global_load_lds_dwordx4 v137, s[30:31]
	s_add_i32 m0, s36, 0x2000
	s_nop 0
	global_load_lds_dwordx4 v138, s[30:31]
	s_add_i32 m0, s36, 0x3000
	s_nop 0
	global_load_lds_dwordx4 v139, s[30:31]
	s_add_i32 m0, s36, 0x4000
	s_nop 0
	global_load_lds_dwordx4 v136, s[44:45]
	s_add_i32 m0, s36, 0x5000
	s_nop 0
	global_load_lds_dwordx4 v137, s[44:45]
	s_add_i32 m0, s36, 0x6000
	s_nop 0
	global_load_lds_dwordx4 v138, s[44:45]
	s_add_i32 m0, s36, 0x7000
	s_nop 0
	global_load_lds_dwordx4 v139, s[44:45]
	s_add_u32 s30, s30, 0x80
	s_addc_u32 s31, s31, 0
	s_add_u32 s44, s44, 0x80
	s_addc_u32 s45, s45, 0
	s_setprio 1
	v_mfma_f32_16x16x32_bf16 v[62:65], v[188:191], v[148:151], v[62:65]
	v_mfma_f32_16x16x32_bf16 v[58:61], v[192:195], v[148:151], v[58:61]
	v_mfma_f32_16x16x32_bf16 v[54:57], v[208:211], v[148:151], v[54:57]
	v_mfma_f32_16x16x32_bf16 v[50:53], v[212:215], v[148:151], v[50:53]
	v_mfma_f32_16x16x32_bf16 v[46:49], v[188:191], v[152:155], v[46:49]
	v_mfma_f32_16x16x32_bf16 v[42:45], v[192:195], v[152:155], v[42:45]
	v_mfma_f32_16x16x32_bf16 v[38:41], v[208:211], v[152:155], v[38:41]
	v_mfma_f32_16x16x32_bf16 v[34:37], v[212:215], v[152:155], v[34:37]
	v_mfma_f32_16x16x32_bf16 v[30:33], v[188:191], v[156:159], v[30:33]
	v_mfma_f32_16x16x32_bf16 v[26:29], v[192:195], v[156:159], v[26:29]
	v_mfma_f32_16x16x32_bf16 v[22:25], v[208:211], v[156:159], v[22:25]
	v_mfma_f32_16x16x32_bf16 v[18:21], v[212:215], v[156:159], v[18:21]
	v_mfma_f32_16x16x32_bf16 v[14:17], v[188:191], v[160:163], v[14:17]
	v_mfma_f32_16x16x32_bf16 v[10:13], v[192:195], v[160:163], v[10:13]
	v_mfma_f32_16x16x32_bf16 v[6:9], v[208:211], v[160:163], v[6:9]
	v_mfma_f32_16x16x32_bf16 v[2:5], v[212:215], v[160:163], v[2:5]
	v_mfma_f32_16x16x32_bf16 v[66:69], v[188:191], v[164:167], v[66:69]
	v_mfma_f32_16x16x32_bf16 v[70:73], v[192:195], v[164:167], v[70:73]
	v_mfma_f32_16x16x32_bf16 v[74:77], v[208:211], v[164:167], v[74:77]
	v_mfma_f32_16x16x32_bf16 v[78:81], v[212:215], v[164:167], v[78:81]
	v_mfma_f32_16x16x32_bf16 v[82:85], v[188:191], v[168:171], v[82:85]
	v_mfma_f32_16x16x32_bf16 v[86:89], v[192:195], v[168:171], v[86:89]
	v_mfma_f32_16x16x32_bf16 v[90:93], v[208:211], v[168:171], v[90:93]
	v_mfma_f32_16x16x32_bf16 v[94:97], v[212:215], v[168:171], v[94:97]
	v_mfma_f32_16x16x32_bf16 v[98:101], v[188:191], v[174:177], v[98:101]
	v_mfma_f32_16x16x32_bf16 v[102:105], v[192:195], v[174:177], v[102:105]
	v_mfma_f32_16x16x32_bf16 v[106:109], v[208:211], v[174:177], v[106:109]
	v_mfma_f32_16x16x32_bf16 v[110:113], v[212:215], v[174:177], v[110:113]
	v_mfma_f32_16x16x32_bf16 v[114:117], v[188:191], v[182:185], v[114:117]
	v_mfma_f32_16x16x32_bf16 v[118:121], v[192:195], v[182:185], v[118:121]
	v_mfma_f32_16x16x32_bf16 v[122:125], v[208:211], v[182:185], v[122:125]
	v_mfma_f32_16x16x32_bf16 v[126:129], v[212:215], v[182:185], v[126:129]
	s_setprio 0
	s_waitcnt vmcnt(0)
	s_barrier
	s_add_i32 m0, s36, 0x8000
	s_nop 0
	global_load_lds_dwordx4 v136, s[34:35]
	s_add_i32 m0, s36, 0x9000
	s_nop 0
	global_load_lds_dwordx4 v137, s[34:35]
	s_add_i32 m0, s36, 0xa000
	s_nop 0
	global_load_lds_dwordx4 v138, s[34:35]
	s_add_i32 m0, s36, 0xb000
	s_nop 0
	global_load_lds_dwordx4 v139, s[34:35]
	s_add_u32 s34, s34, 0x80
	s_addc_u32 s35, s35, 0
	ds_read_b128 v[148:151], v140 offset:0
	ds_read_b128 v[152:155], v140 offset:2048
	ds_read_b128 v[156:159], v140 offset:4096
	ds_read_b128 v[160:163], v140 offset:6144
	ds_read_b128 v[164:167], v140 offset:16384
	ds_read_b128 v[168:171], v140 offset:18432
	ds_read_b128 v[174:177], v140 offset:20480
	ds_read_b128 v[182:185], v140 offset:22528
	ds_read_b128 v[188:191], v142 offset:49152
	ds_read_b128 v[192:195], v142 offset:51200
	ds_read_b128 v[208:211], v142 offset:53248
	ds_read_b128 v[212:215], v142 offset:55296
	s_waitcnt lgkmcnt(0)
	s_setprio 1
	v_mfma_f32_16x16x32_bf16 v[62:65], v[188:191], v[148:151], v[62:65]
	v_mfma_f32_16x16x32_bf16 v[58:61], v[192:195], v[148:151], v[58:61]
	v_mfma_f32_16x16x32_bf16 v[54:57], v[208:211], v[148:151], v[54:57]
	v_mfma_f32_16x16x32_bf16 v[50:53], v[212:215], v[148:151], v[50:53]
	v_mfma_f32_16x16x32_bf16 v[46:49], v[188:191], v[152:155], v[46:49]
	v_mfma_f32_16x16x32_bf16 v[42:45], v[192:195], v[152:155], v[42:45]
	v_mfma_f32_16x16x32_bf16 v[38:41], v[208:211], v[152:155], v[38:41]
	v_mfma_f32_16x16x32_bf16 v[34:37], v[212:215], v[152:155], v[34:37]
	v_mfma_f32_16x16x32_bf16 v[30:33], v[188:191], v[156:159], v[30:33]
	v_mfma_f32_16x16x32_bf16 v[26:29], v[192:195], v[156:159], v[26:29]
	v_mfma_f32_16x16x32_bf16 v[22:25], v[208:211], v[156:159], v[22:25]
	v_mfma_f32_16x16x32_bf16 v[18:21], v[212:215], v[156:159], v[18:21]
	v_mfma_f32_16x16x32_bf16 v[14:17], v[188:191], v[160:163], v[14:17]
	v_mfma_f32_16x16x32_bf16 v[10:13], v[192:195], v[160:163], v[10:13]
	v_mfma_f32_16x16x32_bf16 v[6:9], v[208:211], v[160:163], v[6:9]
	v_mfma_f32_16x16x32_bf16 v[2:5], v[212:215], v[160:163], v[2:5]
	v_mfma_f32_16x16x32_bf16 v[66:69], v[188:191], v[164:167], v[66:69]
	v_mfma_f32_16x16x32_bf16 v[70:73], v[192:195], v[164:167], v[70:73]
	v_mfma_f32_16x16x32_bf16 v[74:77], v[208:211], v[164:167], v[74:77]
	v_mfma_f32_16x16x32_bf16 v[78:81], v[212:215], v[164:167], v[78:81]
	v_mfma_f32_16x16x32_bf16 v[82:85], v[188:191], v[168:171], v[82:85]
	v_mfma_f32_16x16x32_bf16 v[86:89], v[192:195], v[168:171], v[86:89]
	v_mfma_f32_16x16x32_bf16 v[90:93], v[208:211], v[168:171], v[90:93]
	v_mfma_f32_16x16x32_bf16 v[94:97], v[212:215], v[168:171], v[94:97]
	v_mfma_f32_16x16x32_bf16 v[98:101], v[188:191], v[174:177], v[98:101]
	v_mfma_f32_16x16x32_bf16 v[102:105], v[192:195], v[174:177], v[102:105]
	v_mfma_f32_16x16x32_bf16 v[106:109], v[208:211], v[174:177], v[106:109]
	v_mfma_f32_16x16x32_bf16 v[110:113], v[212:215], v[174:177], v[110:113]
	v_mfma_f32_16x16x32_bf16 v[114:117], v[188:191], v[182:185], v[114:117]
	v_mfma_f32_16x16x32_bf16 v[118:121], v[192:195], v[182:185], v[118:121]
	v_mfma_f32_16x16x32_bf16 v[122:125], v[208:211], v[182:185], v[122:125]
	v_mfma_f32_16x16x32_bf16 v[126:129], v[212:215], v[182:185], v[126:129]
	s_setprio 0
	ds_read_b128 v[148:151], v141 offset:0
	ds_read_b128 v[152:155], v141 offset:2048
	ds_read_b128 v[156:159], v141 offset:4096
	ds_read_b128 v[160:163], v141 offset:6144
	ds_read_b128 v[164:167], v141 offset:16384
	ds_read_b128 v[168:171], v141 offset:18432
	ds_read_b128 v[174:177], v141 offset:20480
	ds_read_b128 v[182:185], v141 offset:22528
	ds_read_b128 v[188:191], v143 offset:49152
	ds_read_b128 v[192:195], v143 offset:51200
	ds_read_b128 v[208:211], v143 offset:53248
	ds_read_b128 v[212:215], v143 offset:55296
	s_waitcnt lgkmcnt(0)
	s_barrier
	s_add_i32 m0, s36, 0x0
	s_nop 0
	global_load_lds_dwordx4 v136, s[30:31]
	s_add_i32 m0, s36, 0x1000
	s_nop 0
	global_load_lds_dwordx4 v137, s[30:31]
	s_add_i32 m0, s36, 0x2000
	s_nop 0
	global_load_lds_dwordx4 v138, s[30:31]
	s_add_i32 m0, s36, 0x3000
	s_nop 0
	global_load_lds_dwordx4 v139, s[30:31]
	s_add_i32 m0, s36, 0x4000
	s_nop 0
	global_load_lds_dwordx4 v136, s[44:45]
	s_add_i32 m0, s36, 0x5000
	s_nop 0
	global_load_lds_dwordx4 v137, s[44:45]
	s_add_i32 m0, s36, 0x6000
	s_nop 0
	global_load_lds_dwordx4 v138, s[44:45]
	s_add_i32 m0, s36, 0x7000
	s_nop 0
	global_load_lds_dwordx4 v139, s[44:45]
	s_add_u32 s30, s30, 0x80
	s_addc_u32 s31, s31, 0
	s_add_u32 s44, s44, 0x80
	s_addc_u32 s45, s45, 0
	s_setprio 1
	v_mfma_f32_16x16x32_bf16 v[62:65], v[188:191], v[148:151], v[62:65]
	v_mfma_f32_16x16x32_bf16 v[58:61], v[192:195], v[148:151], v[58:61]
	v_mfma_f32_16x16x32_bf16 v[54:57], v[208:211], v[148:151], v[54:57]
	v_mfma_f32_16x16x32_bf16 v[50:53], v[212:215], v[148:151], v[50:53]
	v_mfma_f32_16x16x32_bf16 v[46:49], v[188:191], v[152:155], v[46:49]
	v_mfma_f32_16x16x32_bf16 v[42:45], v[192:195], v[152:155], v[42:45]
	v_mfma_f32_16x16x32_bf16 v[38:41], v[208:211], v[152:155], v[38:41]
	v_mfma_f32_16x16x32_bf16 v[34:37], v[212:215], v[152:155], v[34:37]
	v_mfma_f32_16x16x32_bf16 v[30:33], v[188:191], v[156:159], v[30:33]
	v_mfma_f32_16x16x32_bf16 v[26:29], v[192:195], v[156:159], v[26:29]
	v_mfma_f32_16x16x32_bf16 v[22:25], v[208:211], v[156:159], v[22:25]
	v_mfma_f32_16x16x32_bf16 v[18:21], v[212:215], v[156:159], v[18:21]
	v_mfma_f32_16x16x32_bf16 v[14:17], v[188:191], v[160:163], v[14:17]
	v_mfma_f32_16x16x32_bf16 v[10:13], v[192:195], v[160:163], v[10:13]
	v_mfma_f32_16x16x32_bf16 v[6:9], v[208:211], v[160:163], v[6:9]
	v_mfma_f32_16x16x32_bf16 v[2:5], v[212:215], v[160:163], v[2:5]
	v_mfma_f32_16x16x32_bf16 v[66:69], v[188:191], v[164:167], v[66:69]
	v_mfma_f32_16x16x32_bf16 v[70:73], v[192:195], v[164:167], v[70:73]
	v_mfma_f32_16x16x32_bf16 v[74:77], v[208:211], v[164:167], v[74:77]
	v_mfma_f32_16x16x32_bf16 v[78:81], v[212:215], v[164:167], v[78:81]
	v_mfma_f32_16x16x32_bf16 v[82:85], v[188:191], v[168:171], v[82:85]
	v_mfma_f32_16x16x32_bf16 v[86:89], v[192:195], v[168:171], v[86:89]
	v_mfma_f32_16x16x32_bf16 v[90:93], v[208:211], v[168:171], v[90:93]
	v_mfma_f32_16x16x32_bf16 v[94:97], v[212:215], v[168:171], v[94:97]
	v_mfma_f32_16x16x32_bf16 v[98:101], v[188:191], v[174:177], v[98:101]
	v_mfma_f32_16x16x32_bf16 v[102:105], v[192:195], v[174:177], v[102:105]
	v_mfma_f32_16x16x32_bf16 v[106:109], v[208:211], v[174:177], v[106:109]
	v_mfma_f32_16x16x32_bf16 v[110:113], v[212:215], v[174:177], v[110:113]
	v_mfma_f32_16x16x32_bf16 v[114:117], v[188:191], v[182:185], v[114:117]
	v_mfma_f32_16x16x32_bf16 v[118:121], v[192:195], v[182:185], v[118:121]
	v_mfma_f32_16x16x32_bf16 v[122:125], v[208:211], v[182:185], v[122:125]
	v_mfma_f32_16x16x32_bf16 v[126:129], v[212:215], v[182:185], v[126:129]
	s_setprio 0
	s_add_i32 s37, s37, -1
	s_cmp_lg_u32 s37, 0
	s_cbranch_scc1 .Lr2o_k
	s_waitcnt vmcnt(0)
	s_barrier
	s_add_i32 m0, s36, 0xc000
	s_nop 0
	global_load_lds_dwordx4 v136, s[34:35]
	s_add_i32 m0, s36, 0xd000
	s_nop 0
	global_load_lds_dwordx4 v137, s[34:35]
	s_add_i32 m0, s36, 0xe000
	s_nop 0
	global_load_lds_dwordx4 v138, s[34:35]
	s_add_i32 m0, s36, 0xf000
	s_nop 0
	global_load_lds_dwordx4 v139, s[34:35]
	s_add_u32 s34, s34, 0x80
	s_addc_u32 s35, s35, 0
	ds_read_b128 v[148:151], v140 offset:0
	ds_read_b128 v[152:155], v140 offset:2048
	ds_read_b128 v[156:159], v140 offset:4096
	ds_read_b128 v[160:163], v140 offset:6144
	ds_read_b128 v[164:167], v140 offset:16384
	ds_read_b128 v[168:171], v140 offset:18432
	ds_read_b128 v[174:177], v140 offset:20480
	ds_read_b128 v[182:185], v140 offset:22528
	ds_read_b128 v[188:191], v142 offset:32768
	ds_read_b128 v[192:195], v142 offset:34816
	ds_read_b128 v[208:211], v142 offset:36864
	ds_read_b128 v[212:215], v142 offset:38912
	s_waitcnt lgkmcnt(0)
	s_setprio 1
	v_mfma_f32_16x16x32_bf16 v[62:65], v[188:191], v[148:151], v[62:65]
	v_mfma_f32_16x16x32_bf16 v[58:61], v[192:195], v[148:151], v[58:61]
	v_mfma_f32_16x16x32_bf16 v[54:57], v[208:211], v[148:151], v[54:57]
	v_mfma_f32_16x16x32_bf16 v[50:53], v[212:215], v[148:151], v[50:53]
	v_mfma_f32_16x16x32_bf16 v[46:49], v[188:191], v[152:155], v[46:49]
	v_mfma_f32_16x16x32_bf16 v[42:45], v[192:195], v[152:155], v[42:45]
	v_mfma_f32_16x16x32_bf16 v[38:41], v[208:211], v[152:155], v[38:41]
	v_mfma_f32_16x16x32_bf16 v[34:37], v[212:215], v[152:155], v[34:37]
	v_mfma_f32_16x16x32_bf16 v[30:33], v[188:191], v[156:159], v[30:33]
	v_mfma_f32_16x16x32_bf16 v[26:29], v[192:195], v[156:159], v[26:29]
	v_mfma_f32_16x16x32_bf16 v[22:25], v[208:211], v[156:159], v[22:25]
	v_mfma_f32_16x16x32_bf16 v[18:21], v[212:215], v[156:159], v[18:21]
	v_mfma_f32_16x16x32_bf16 v[14:17], v[188:191], v[160:163], v[14:17]
	v_mfma_f32_16x16x32_bf16 v[10:13], v[192:195], v[160:163], v[10:13]
	v_mfma_f32_16x16x32_bf16 v[6:9], v[208:211], v[160:163], v[6:9]
	v_mfma_f32_16x16x32_bf16 v[2:5], v[212:215], v[160:163], v[2:5]
	v_mfma_f32_16x16x32_bf16 v[66:69], v[188:191], v[164:167], v[66:69]
	v_mfma_f32_16x16x32_bf16 v[70:73], v[192:195], v[164:167], v[70:73]
	v_mfma_f32_16x16x32_bf16 v[74:77], v[208:211], v[164:167], v[74:77]
	v_mfma_f32_16x16x32_bf16 v[78:81], v[212:215], v[164:167], v[78:81]
	v_mfma_f32_16x16x32_bf16 v[82:85], v[188:191], v[168:171], v[82:85]
	v_mfma_f32_16x16x32_bf16 v[86:89], v[192:195], v[168:171], v[86:89]
	v_mfma_f32_16x16x32_bf16 v[90:93], v[208:211], v[168:171], v[90:93]
	v_mfma_f32_16x16x32_bf16 v[94:97], v[212:215], v[168:171], v[94:97]
	v_mfma_f32_16x16x32_bf16 v[98:101], v[188:191], v[174:177], v[98:101]
	v_mfma_f32_16x16x32_bf16 v[102:105], v[192:195], v[174:177], v[102:105]
	v_mfma_f32_16x16x32_bf16 v[106:109], v[208:211], v[174:177], v[106:109]
	v_mfma_f32_16x16x32_bf16 v[110:113], v[212:215], v[174:177], v[110:113]
	v_mfma_f32_16x16x32_bf16 v[114:117], v[188:191], v[182:185], v[114:117]
	v_mfma_f32_16x16x32_bf16 v[118:121], v[192:195], v[182:185], v[118:121]
	v_mfma_f32_16x16x32_bf16 v[122:125], v[208:211], v[182:185], v[122:125]
	v_mfma_f32_16x16x32_bf16 v[126:129], v[212:215], v[182:185], v[126:129]
	s_setprio 0
	ds_read_b128 v[148:151], v141 offset:0
	ds_read_b128 v[152:155], v141 offset:2048
	ds_read_b128 v[156:159], v141 offset:4096
	ds_read_b128 v[160:163], v141 offset:6144
	ds_read_b128 v[164:167], v141 offset:16384
	ds_read_b128 v[168:171], v141 offset:18432
	ds_read_b128 v[174:177], v141 offset:20480
	ds_read_b128 v[182:185], v141 offset:22528
	ds_read_b128 v[188:191], v143 offset:32768
	ds_read_b128 v[192:195], v143 offset:34816
	ds_read_b128 v[208:211], v143 offset:36864
	ds_read_b128 v[212:215], v143 offset:38912
	s_waitcnt lgkmcnt(0)
	s_barrier
	s_add_i32 m0, s36, 0x0
	s_nop 0
	global_load_lds_dwordx4 v136, s[30:31]
	s_add_i32 m0, s36, 0x1000
	s_nop 0
	global_load_lds_dwordx4 v137, s[30:31]
	s_add_i32 m0, s36, 0x2000
	s_nop 0
	global_load_lds_dwordx4 v138, s[30:31]
	s_add_i32 m0, s36, 0x3000
	s_nop 0
	global_load_lds_dwordx4 v139, s[30:31]
	s_add_i32 m0, s36, 0x4000
	s_nop 0
	global_load_lds_dwordx4 v136, s[44:45]
	s_add_i32 m0, s36, 0x5000
	s_nop 0
	global_load_lds_dwordx4 v137, s[44:45]
	s_add_i32 m0, s36, 0x6000
	s_nop 0
	global_load_lds_dwordx4 v138, s[44:45]
	s_add_i32 m0, s36, 0x7000
	s_nop 0
	global_load_lds_dwordx4 v139, s[44:45]
	s_add_u32 s30, s30, 0x80
	s_addc_u32 s31, s31, 0
	s_add_u32 s44, s44, 0x80
	s_addc_u32 s45, s45, 0
	s_setprio 1
	v_mfma_f32_16x16x32_bf16 v[62:65], v[188:191], v[148:151], v[62:65]
	v_mfma_f32_16x16x32_bf16 v[58:61], v[192:195], v[148:151], v[58:61]
	v_mfma_f32_16x16x32_bf16 v[54:57], v[208:211], v[148:151], v[54:57]
	v_mfma_f32_16x16x32_bf16 v[50:53], v[212:215], v[148:151], v[50:53]
	v_mfma_f32_16x16x32_bf16 v[46:49], v[188:191], v[152:155], v[46:49]
	v_mfma_f32_16x16x32_bf16 v[42:45], v[192:195], v[152:155], v[42:45]
	v_mfma_f32_16x16x32_bf16 v[38:41], v[208:211], v[152:155], v[38:41]
	v_mfma_f32_16x16x32_bf16 v[34:37], v[212:215], v[152:155], v[34:37]
	v_mfma_f32_16x16x32_bf16 v[30:33], v[188:191], v[156:159], v[30:33]
	v_mfma_f32_16x16x32_bf16 v[26:29], v[192:195], v[156:159], v[26:29]
	v_mfma_f32_16x16x32_bf16 v[22:25], v[208:211], v[156:159], v[22:25]
	v_mfma_f32_16x16x32_bf16 v[18:21], v[212:215], v[156:159], v[18:21]
	v_mfma_f32_16x16x32_bf16 v[14:17], v[188:191], v[160:163], v[14:17]
	v_mfma_f32_16x16x32_bf16 v[10:13], v[192:195], v[160:163], v[10:13]
	v_mfma_f32_16x16x32_bf16 v[6:9], v[208:211], v[160:163], v[6:9]
	v_mfma_f32_16x16x32_bf16 v[2:5], v[212:215], v[160:163], v[2:5]
	v_mfma_f32_16x16x32_bf16 v[66:69], v[188:191], v[164:167], v[66:69]
	v_mfma_f32_16x16x32_bf16 v[70:73], v[192:195], v[164:167], v[70:73]
	v_mfma_f32_16x16x32_bf16 v[74:77], v[208:211], v[164:167], v[74:77]
	v_mfma_f32_16x16x32_bf16 v[78:81], v[212:215], v[164:167], v[78:81]
	v_mfma_f32_16x16x32_bf16 v[82:85], v[188:191], v[168:171], v[82:85]
	v_mfma_f32_16x16x32_bf16 v[86:89], v[192:195], v[168:171], v[86:89]
	v_mfma_f32_16x16x32_bf16 v[90:93], v[208:211], v[168:171], v[90:93]
	v_mfma_f32_16x16x32_bf16 v[94:97], v[212:215], v[168:171], v[94:97]
	v_mfma_f32_16x16x32_bf16 v[98:101], v[188:191], v[174:177], v[98:101]
	v_mfma_f32_16x16x32_bf16 v[102:105], v[192:195], v[174:177], v[102:105]
	v_mfma_f32_16x16x32_bf16 v[106:109], v[208:211], v[174:177], v[106:109]
	v_mfma_f32_16x16x32_bf16 v[110:113], v[212:215], v[174:177], v[110:113]
	v_mfma_f32_16x16x32_bf16 v[114:117], v[188:191], v[182:185], v[114:117]
	v_mfma_f32_16x16x32_bf16 v[118:121], v[192:195], v[182:185], v[118:121]
	v_mfma_f32_16x16x32_bf16 v[122:125], v[208:211], v[182:185], v[122:125]
	v_mfma_f32_16x16x32_bf16 v[126:129], v[212:215], v[182:185], v[126:129]
	s_setprio 0
	s_waitcnt vmcnt(0)
	s_barrier
	ds_read_b128 v[148:151], v140 offset:0
	ds_read_b128 v[152:155], v140 offset:2048
	ds_read_b128 v[156:159], v140 offset:4096
	ds_read_b128 v[160:163], v140 offset:6144
	ds_read_b128 v[164:167], v140 offset:16384
	ds_read_b128 v[168:171], v140 offset:18432
	ds_read_b128 v[174:177], v140 offset:20480
	ds_read_b128 v[182:185], v140 offset:22528
	ds_read_b128 v[188:191], v142 offset:49152
	ds_read_b128 v[192:195], v142 offset:51200
	ds_read_b128 v[208:211], v142 offset:53248
	ds_read_b128 v[212:215], v142 offset:55296
	s_waitcnt lgkmcnt(0)
	s_setprio 1
	v_mfma_f32_16x16x32_bf16 v[62:65], v[188:191], v[148:151], v[62:65]
	v_mfma_f32_16x16x32_bf16 v[58:61], v[192:195], v[148:151], v[58:61]
	v_mfma_f32_16x16x32_bf16 v[54:57], v[208:211], v[148:151], v[54:57]
	v_mfma_f32_16x16x32_bf16 v[50:53], v[212:215], v[148:151], v[50:53]
	v_mfma_f32_16x16x32_bf16 v[46:49], v[188:191], v[152:155], v[46:49]
	v_mfma_f32_16x16x32_bf16 v[42:45], v[192:195], v[152:155], v[42:45]
	v_mfma_f32_16x16x32_bf16 v[38:41], v[208:211], v[152:155], v[38:41]
	v_mfma_f32_16x16x32_bf16 v[34:37], v[212:215], v[152:155], v[34:37]
	v_mfma_f32_16x16x32_bf16 v[30:33], v[188:191], v[156:159], v[30:33]
	v_mfma_f32_16x16x32_bf16 v[26:29], v[192:195], v[156:159], v[26:29]
	v_mfma_f32_16x16x32_bf16 v[22:25], v[208:211], v[156:159], v[22:25]
	v_mfma_f32_16x16x32_bf16 v[18:21], v[212:215], v[156:159], v[18:21]
	v_mfma_f32_16x16x32_bf16 v[14:17], v[188:191], v[160:163], v[14:17]
	v_mfma_f32_16x16x32_bf16 v[10:13], v[192:195], v[160:163], v[10:13]
	v_mfma_f32_16x16x32_bf16 v[6:9], v[208:211], v[160:163], v[6:9]
	v_mfma_f32_16x16x32_bf16 v[2:5], v[212:215], v[160:163], v[2:5]
	v_mfma_f32_16x16x32_bf16 v[66:69], v[188:191], v[164:167], v[66:69]
	v_mfma_f32_16x16x32_bf16 v[70:73], v[192:195], v[164:167], v[70:73]
	v_mfma_f32_16x16x32_bf16 v[74:77], v[208:211], v[164:167], v[74:77]
	v_mfma_f32_16x16x32_bf16 v[78:81], v[212:215], v[164:167], v[78:81]
	v_mfma_f32_16x16x32_bf16 v[82:85], v[188:191], v[168:171], v[82:85]
	v_mfma_f32_16x16x32_bf16 v[86:89], v[192:195], v[168:171], v[86:89]
	v_mfma_f32_16x16x32_bf16 v[90:93], v[208:211], v[168:171], v[90:93]
	v_mfma_f32_16x16x32_bf16 v[94:97], v[212:215], v[168:171], v[94:97]
	v_mfma_f32_16x16x32_bf16 v[98:101], v[188:191], v[174:177], v[98:101]
	v_mfma_f32_16x16x32_bf16 v[102:105], v[192:195], v[174:177], v[102:105]
	v_mfma_f32_16x16x32_bf16 v[106:109], v[208:211], v[174:177], v[106:109]
	v_mfma_f32_16x16x32_bf16 v[110:113], v[212:215], v[174:177], v[110:113]
	v_mfma_f32_16x16x32_bf16 v[114:117], v[188:191], v[182:185], v[114:117]
	v_mfma_f32_16x16x32_bf16 v[118:121], v[192:195], v[182:185], v[118:121]
	v_mfma_f32_16x16x32_bf16 v[122:125], v[208:211], v[182:185], v[122:125]
	v_mfma_f32_16x16x32_bf16 v[126:129], v[212:215], v[182:185], v[126:129]
	s_setprio 0
	ds_read_b128 v[148:151], v141 offset:0
	ds_read_b128 v[152:155], v141 offset:2048
	ds_read_b128 v[156:159], v141 offset:4096
	ds_read_b128 v[160:163], v141 offset:6144
	ds_read_b128 v[164:167], v141 offset:16384
	ds_read_b128 v[168:171], v141 offset:18432
	ds_read_b128 v[174:177], v141 offset:20480
	ds_read_b128 v[182:185], v141 offset:22528
	ds_read_b128 v[188:191], v143 offset:49152
	ds_read_b128 v[192:195], v143 offset:51200
	ds_read_b128 v[208:211], v143 offset:53248
	ds_read_b128 v[212:215], v143 offset:55296
	s_waitcnt lgkmcnt(0)
	s_setprio 1
	v_mfma_f32_16x16x32_bf16 v[62:65], v[188:191], v[148:151], v[62:65]
	v_mfma_f32_16x16x32_bf16 v[58:61], v[192:195], v[148:151], v[58:61]
	v_mfma_f32_16x16x32_bf16 v[54:57], v[208:211], v[148:151], v[54:57]
	v_mfma_f32_16x16x32_bf16 v[50:53], v[212:215], v[148:151], v[50:53]
	v_mfma_f32_16x16x32_bf16 v[46:49], v[188:191], v[152:155], v[46:49]
	v_mfma_f32_16x16x32_bf16 v[42:45], v[192:195], v[152:155], v[42:45]
	v_mfma_f32_16x16x32_bf16 v[38:41], v[208:211], v[152:155], v[38:41]
	v_mfma_f32_16x16x32_bf16 v[34:37], v[212:215], v[152:155], v[34:37]
	v_mfma_f32_16x16x32_bf16 v[30:33], v[188:191], v[156:159], v[30:33]
	v_mfma_f32_16x16x32_bf16 v[26:29], v[192:195], v[156:159], v[26:29]
	v_mfma_f32_16x16x32_bf16 v[22:25], v[208:211], v[156:159], v[22:25]
	v_mfma_f32_16x16x32_bf16 v[18:21], v[212:215], v[156:159], v[18:21]
	v_mfma_f32_16x16x32_bf16 v[14:17], v[188:191], v[160:163], v[14:17]
	v_mfma_f32_16x16x32_bf16 v[10:13], v[192:195], v[160:163], v[10:13]
	v_mfma_f32_16x16x32_bf16 v[6:9], v[208:211], v[160:163], v[6:9]
	v_mfma_f32_16x16x32_bf16 v[2:5], v[212:215], v[160:163], v[2:5]
	v_mfma_f32_16x16x32_bf16 v[66:69], v[188:191], v[164:167], v[66:69]
	v_mfma_f32_16x16x32_bf16 v[70:73], v[192:195], v[164:167], v[70:73]
	v_mfma_f32_16x16x32_bf16 v[74:77], v[208:211], v[164:167], v[74:77]
	v_mfma_f32_16x16x32_bf16 v[78:81], v[212:215], v[164:167], v[78:81]
	v_mfma_f32_16x16x32_bf16 v[82:85], v[188:191], v[168:171], v[82:85]
	v_mfma_f32_16x16x32_bf16 v[86:89], v[192:195], v[168:171], v[86:89]
	v_mfma_f32_16x16x32_bf16 v[90:93], v[208:211], v[168:171], v[90:93]
	v_mfma_f32_16x16x32_bf16 v[94:97], v[212:215], v[168:171], v[94:97]
	v_mfma_f32_16x16x32_bf16 v[98:101], v[188:191], v[174:177], v[98:101]
	v_mfma_f32_16x16x32_bf16 v[102:105], v[192:195], v[174:177], v[102:105]
	v_mfma_f32_16x16x32_bf16 v[106:109], v[208:211], v[174:177], v[106:109]
	v_mfma_f32_16x16x32_bf16 v[110:113], v[212:215], v[174:177], v[110:113]
	v_mfma_f32_16x16x32_bf16 v[114:117], v[188:191], v[182:185], v[114:117]
	v_mfma_f32_16x16x32_bf16 v[118:121], v[192:195], v[182:185], v[118:121]
	v_mfma_f32_16x16x32_bf16 v[122:125], v[208:211], v[182:185], v[122:125]
	v_mfma_f32_16x16x32_bf16 v[126:129], v[212:215], v[182:185], v[126:129]
	s_setprio 0
	v_lshrrev_b32_e32 v144, 7, v196
	v_and_b32_e32 v145, 15, v196
	v_lshl_or_b32 v144, v144, 6, v145
	v_lshlrev_b32_e32 v144, 12, v144
	v_bfe_u32 v145, v196, 6, 1
	v_bfe_u32 v146, v196, 4, 2
	v_lshlrev_b32_e32 v145, 8, v145
	v_lshl_or_b32 v145, v146, 4, v145
	v_add_u32_e32 v136, v144, v145
	v_add_u32_e32 v137, 0x10000, v136
	v_add_u32_e32 v138, 0x20000, v136
	v_add_u32_e32 v139, 0x30000, v136
	s_nop 7
	s_nop 7
	s_nop 7
	global_load_dwordx4 v[148:151], v136, s[40:41] offset:0
	global_load_dwordx4 v[152:155], v136, s[40:41] offset:64
	global_load_dwordx4 v[156:159], v136, s[40:41] offset:128
	global_load_dwordx4 v[160:163], v136, s[40:41] offset:192
	global_load_dwordx4 v[164:167], v137, s[40:41] offset:0
	global_load_dwordx4 v[168:171], v137, s[40:41] offset:64
	global_load_dwordx4 v[174:177], v137, s[40:41] offset:128
	global_load_dwordx4 v[182:185], v137, s[40:41] offset:192
	global_load_dwordx4 v[188:191], v138, s[40:41] offset:0
	global_load_dwordx4 v[192:195], v138, s[40:41] offset:64
	global_load_dwordx4 v[208:211], v138, s[40:41] offset:128
	global_load_dwordx4 v[212:215], v138, s[40:41] offset:192
	global_load_dwordx4 v[216:219], v139, s[40:41] offset:0
	global_load_dwordx4 v[220:223], v139, s[40:41] offset:64
	global_load_dwordx4 v[242:245], v139, s[40:41] offset:128
	global_load_dwordx4 v[144:147], v139, s[40:41] offset:192
	s_waitcnt vmcnt(0)
	v_pk_add_f32 v[62:63], v[62:63], v[148:149]
	v_pk_add_f32 v[64:65], v[64:65], v[150:151]
	v_pk_add_f32 v[58:59], v[58:59], v[152:153]
	v_pk_add_f32 v[60:61], v[60:61], v[154:155]
	v_pk_add_f32 v[54:55], v[54:55], v[156:157]
	v_pk_add_f32 v[56:57], v[56:57], v[158:159]
	v_pk_add_f32 v[50:51], v[50:51], v[160:161]
	v_pk_add_f32 v[52:53], v[52:53], v[162:163]
	v_pk_add_f32 v[46:47], v[46:47], v[164:165]
	v_pk_add_f32 v[48:49], v[48:49], v[166:167]
	v_pk_add_f32 v[42:43], v[42:43], v[168:169]
	v_pk_add_f32 v[44:45], v[44:45], v[170:171]
	v_pk_add_f32 v[38:39], v[38:39], v[174:175]
	v_pk_add_f32 v[40:41], v[40:41], v[176:177]
	v_pk_add_f32 v[34:35], v[34:35], v[182:183]
	v_pk_add_f32 v[36:37], v[36:37], v[184:185]
	v_pk_add_f32 v[30:31], v[30:31], v[188:189]
	v_pk_add_f32 v[32:33], v[32:33], v[190:191]
	v_pk_add_f32 v[26:27], v[26:27], v[192:193]
	v_pk_add_f32 v[28:29], v[28:29], v[194:195]
	v_pk_add_f32 v[22:23], v[22:23], v[208:209]
	v_pk_add_f32 v[24:25], v[24:25], v[210:211]
	v_pk_add_f32 v[18:19], v[18:19], v[212:213]
	v_pk_add_f32 v[20:21], v[20:21], v[214:215]
	v_pk_add_f32 v[14:15], v[14:15], v[216:217]
	v_pk_add_f32 v[16:17], v[16:17], v[218:219]
	v_pk_add_f32 v[10:11], v[10:11], v[220:221]
	v_pk_add_f32 v[12:13], v[12:13], v[222:223]
	v_pk_add_f32 v[6:7], v[6:7], v[242:243]
	v_pk_add_f32 v[8:9], v[8:9], v[244:245]
	v_pk_add_f32 v[2:3], v[2:3], v[144:145]
	v_pk_add_f32 v[4:5], v[4:5], v[146:147]
	global_load_dwordx4 v[148:151], v136, s[42:43] offset:0
	global_load_dwordx4 v[152:155], v136, s[42:43] offset:64
	global_load_dwordx4 v[156:159], v136, s[42:43] offset:128
	global_load_dwordx4 v[160:163], v136, s[42:43] offset:192
	global_load_dwordx4 v[164:167], v137, s[42:43] offset:0
	global_load_dwordx4 v[168:171], v137, s[42:43] offset:64
	global_load_dwordx4 v[174:177], v137, s[42:43] offset:128
	global_load_dwordx4 v[182:185], v137, s[42:43] offset:192
	global_load_dwordx4 v[188:191], v138, s[42:43] offset:0
	global_load_dwordx4 v[192:195], v138, s[42:43] offset:64
	global_load_dwordx4 v[208:211], v138, s[42:43] offset:128
	global_load_dwordx4 v[212:215], v138, s[42:43] offset:192
	global_load_dwordx4 v[216:219], v139, s[42:43] offset:0
	global_load_dwordx4 v[220:223], v139, s[42:43] offset:64
	global_load_dwordx4 v[242:245], v139, s[42:43] offset:128
	global_load_dwordx4 v[144:147], v139, s[42:43] offset:192
	global_store_dwordx4 v136, v[62:65], s[40:41] offset:0
	global_store_dwordx4 v136, v[58:61], s[40:41] offset:64
	global_store_dwordx4 v136, v[54:57], s[40:41] offset:128
	global_store_dwordx4 v136, v[50:53], s[40:41] offset:192
	global_store_dwordx4 v137, v[46:49], s[40:41] offset:0
	global_store_dwordx4 v137, v[42:45], s[40:41] offset:64
	global_store_dwordx4 v137, v[38:41], s[40:41] offset:128
	global_store_dwordx4 v137, v[34:37], s[40:41] offset:192
	global_store_dwordx4 v138, v[30:33], s[40:41] offset:0
	global_store_dwordx4 v138, v[26:29], s[40:41] offset:64
	global_store_dwordx4 v138, v[22:25], s[40:41] offset:128
	global_store_dwordx4 v138, v[18:21], s[40:41] offset:192
	global_store_dwordx4 v139, v[14:17], s[40:41] offset:0
	global_store_dwordx4 v139, v[10:13], s[40:41] offset:64
	global_store_dwordx4 v139, v[6:9], s[40:41] offset:128
	global_store_dwordx4 v139, v[2:5], s[40:41] offset:192
	s_waitcnt vmcnt(0)
	v_pk_add_f32 v[66:67], v[66:67], v[148:149]
	v_pk_add_f32 v[68:69], v[68:69], v[150:151]
	v_pk_add_f32 v[70:71], v[70:71], v[152:153]
	v_pk_add_f32 v[72:73], v[72:73], v[154:155]
	v_pk_add_f32 v[74:75], v[74:75], v[156:157]
	v_pk_add_f32 v[76:77], v[76:77], v[158:159]
	v_pk_add_f32 v[78:79], v[78:79], v[160:161]
	v_pk_add_f32 v[80:81], v[80:81], v[162:163]
	v_pk_add_f32 v[82:83], v[82:83], v[164:165]
	v_pk_add_f32 v[84:85], v[84:85], v[166:167]
	v_pk_add_f32 v[86:87], v[86:87], v[168:169]
	v_pk_add_f32 v[88:89], v[88:89], v[170:171]
	v_pk_add_f32 v[90:91], v[90:91], v[174:175]
	v_pk_add_f32 v[92:93], v[92:93], v[176:177]
	v_pk_add_f32 v[94:95], v[94:95], v[182:183]
	v_pk_add_f32 v[96:97], v[96:97], v[184:185]
	v_pk_add_f32 v[98:99], v[98:99], v[188:189]
	v_pk_add_f32 v[100:101], v[100:101], v[190:191]
	v_pk_add_f32 v[102:103], v[102:103], v[192:193]
	v_pk_add_f32 v[104:105], v[104:105], v[194:195]
	v_pk_add_f32 v[106:107], v[106:107], v[208:209]
	v_pk_add_f32 v[108:109], v[108:109], v[210:211]
	v_pk_add_f32 v[110:111], v[110:111], v[212:213]
	v_pk_add_f32 v[112:113], v[112:113], v[214:215]
	v_pk_add_f32 v[114:115], v[114:115], v[216:217]
	v_pk_add_f32 v[116:117], v[116:117], v[218:219]
	v_pk_add_f32 v[118:119], v[118:119], v[220:221]
	v_pk_add_f32 v[120:121], v[120:121], v[222:223]
	v_pk_add_f32 v[122:123], v[122:123], v[242:243]
	v_pk_add_f32 v[124:125], v[124:125], v[244:245]
	v_pk_add_f32 v[126:127], v[126:127], v[144:145]
	v_pk_add_f32 v[128:129], v[128:129], v[146:147]
	global_store_dwordx4 v136, v[66:69], s[42:43] offset:0
	global_store_dwordx4 v136, v[70:73], s[42:43] offset:64
	global_store_dwordx4 v136, v[74:77], s[42:43] offset:128
	global_store_dwordx4 v136, v[78:81], s[42:43] offset:192
	global_store_dwordx4 v137, v[82:85], s[42:43] offset:0
	global_store_dwordx4 v137, v[86:89], s[42:43] offset:64
	global_store_dwordx4 v137, v[90:93], s[42:43] offset:128
	global_store_dwordx4 v137, v[94:97], s[42:43] offset:192
	global_store_dwordx4 v138, v[98:101], s[42:43] offset:0
	global_store_dwordx4 v138, v[102:105], s[42:43] offset:64
	global_store_dwordx4 v138, v[106:109], s[42:43] offset:128
	global_store_dwordx4 v138, v[110:113], s[42:43] offset:192
	global_store_dwordx4 v139, v[114:117], s[42:43] offset:0
	global_store_dwordx4 v139, v[118:121], s[42:43] offset:64
	global_store_dwordx4 v139, v[122:125], s[42:43] offset:128
	global_store_dwordx4 v139, v[126:129], s[42:43] offset:192
	s_branch .LBB0_2421
